# scan compute block: 7 instead of 8 LDS ops per step (ds_read2_b64 for two steps' scale pairs, ds_write2st64_b32 for two steps' y), on top of rms-loop pipelining
# baseline (speedup 1.0000x reference)
.LBB0_1010:
	s_mov_b64 s[78:79], -1
	s_and_b64 vcc, exec, s[70:71]
	s_cbranch_vccz .LBB0_1014
	s_setprio 1
	s_and_b32 s55, s53, 1
	s_lshl_b32 s56, s55, 14
	s_mul_i32 s55, s55, 0xaa00
	v_or_b32_e32 v99, s56, v143
	v_lshl_add_u32 v96, v106, 2, s55
	v_lshl_add_u32 v97, v101, 2, s55
	v_mov_b32_e32 v98, s55
	v_add_u32_e32 v99, 0x15400, v99
	v_add_u32_e32 v240, 0x540, v98
	s_waitcnt vmcnt(0)
	ds_read2_b64 v[232:235], v240 offset1:170
	v_add_u32_e32 v240, 0xaa0, v240
	ds_read_b128 v[170:173], v96 offset:256
	ds_read_b128 v[174:177], v96 offset:512
	ds_read_b128 v[166:169], v96
	ds_read_b128 v[182:185], v96 offset:1024
	ds_read_b128 v[178:181], v96 offset:768
	ds_read_b32 v186, v97 offset:1280
	ds_read_b128 v[194:197], v96 offset:1616
	ds_read_b128 v[198:201], v96 offset:1872
	ds_read_b128 v[190:193], v96 offset:1360
	ds_read_b128 v[206:209], v96 offset:2384
	ds_read_b128 v[202:205], v96 offset:2128
	ds_read_b32 v210, v97 offset:2640
	v_mov_b64_e32 v[48:49], v[92:93]
	v_mov_b64_e32 v[52:53], v[94:95]
	s_waitcnt lgkmcnt(6)
	v_pk_mul_f32 v[58:59], v[52:53], v[170:171] op_sel_hi:[0,1]
	ds_read2_b64 v[236:239], v240 offset1:170
	v_add_u32_e32 v240, 0xaa0, v240
	ds_read_b128 v[32:35], v96 offset:2976
	ds_read_b128 v[36:39], v96 offset:3232
	v_pk_fma_f32 v[58:59], v[52:53], v[172:173], v[58:59] op_sel:[1,0,0]
	ds_read_b128 v[28:31], v96 offset:2720
	ds_read_b128 v[44:47], v96 offset:3744
	v_pk_fma_f32 v[58:59], v[48:49], v[174:175], v[58:59] op_sel_hi:[0,1,1]
	ds_read_b128 v[40:43], v96 offset:3488
	v_pk_fma_f32 v[58:59], v[48:49], v[176:177], v[58:59] op_sel:[1,0,0]
	v_pk_mul_f32 v[64:65], v[186:187], v[182:183] op_sel_hi:[0,1]
	v_pk_mul_f32 v[66:67], v[186:187], v[184:185] op_sel_hi:[0,1]
	v_add_f32_dpp v58, v58, v58 row_ror:8 row_mask:0xf bank_mask:0xf bound_ctrl:1
	v_pk_fma_f32 v[64:65], v[52:53], v[166:167], v[64:65]
	v_pk_fma_f32 v[66:67], v[48:49], v[168:169], v[66:67]
	v_add_f32_dpp v58, v58, v58 row_ror:4 row_mask:0xf bank_mask:0xf bound_ctrl:1
	v_add_f32_dpp v60, v59, v59 row_ror:8 row_mask:0xf bank_mask:0xf bound_ctrl:1
	s_nop 0
	v_add_f32_dpp v58, v58, v58 row_ror:2 row_mask:0xf bank_mask:0xf bound_ctrl:1
	v_fma_f32 v61, v186, v233, v60
	s_nop 0
	v_add_f32_dpp v58, v58, v58 row_ror:1 row_mask:0xf bank_mask:0xf bound_ctrl:1
	v_pk_fma_f32 v[52:53], v[58:59], v[178:179], v[64:65] op_sel_hi:[0,1,1]
	v_pk_fma_f32 v[48:49], v[58:59], v[180:181], v[66:67] op_sel_hi:[0,1,1]
	v_fma_f32 v61, v58, v232, v61
	ds_read_b32 v54, v97 offset:4000
	s_waitcnt lgkmcnt(7)
	v_pk_mul_f32 v[58:59], v[52:53], v[194:195] op_sel_hi:[0,1]
	ds_read_b128 v[170:173], v96 offset:4336
	ds_read_b128 v[174:177], v96 offset:4592
	v_pk_fma_f32 v[58:59], v[52:53], v[196:197], v[58:59] op_sel:[1,0,0]
	ds_read_b128 v[166:169], v96 offset:4080
	ds_read_b128 v[182:185], v96 offset:5104
	v_pk_fma_f32 v[58:59], v[48:49], v[198:199], v[58:59] op_sel_hi:[0,1,1]
	ds_read_b128 v[178:181], v96 offset:4848
	v_pk_fma_f32 v[58:59], v[48:49], v[200:201], v[58:59] op_sel:[1,0,0]
	v_pk_mul_f32 v[64:65], v[210:211], v[206:207] op_sel_hi:[0,1]
	v_pk_mul_f32 v[66:67], v[210:211], v[208:209] op_sel_hi:[0,1]
	v_add_f32_dpp v58, v58, v58 row_ror:8 row_mask:0xf bank_mask:0xf bound_ctrl:1
	v_pk_fma_f32 v[64:65], v[52:53], v[190:191], v[64:65]
	v_pk_fma_f32 v[66:67], v[48:49], v[192:193], v[66:67]
	v_add_f32_dpp v58, v58, v58 row_ror:4 row_mask:0xf bank_mask:0xf bound_ctrl:1
	v_add_f32_dpp v60, v59, v59 row_ror:8 row_mask:0xf bank_mask:0xf bound_ctrl:1
	s_nop 0
	v_add_f32_dpp v58, v58, v58 row_ror:2 row_mask:0xf bank_mask:0xf bound_ctrl:1
	v_fma_f32 v62, v210, v235, v60
	s_nop 0
	v_add_f32_dpp v58, v58, v58 row_ror:1 row_mask:0xf bank_mask:0xf bound_ctrl:1
	v_pk_fma_f32 v[52:53], v[58:59], v[202:203], v[64:65] op_sel_hi:[0,1,1]
	v_pk_fma_f32 v[48:49], v[58:59], v[204:205], v[66:67] op_sel_hi:[0,1,1]
	v_fma_f32 v62, v58, v234, v62
	ds_read_b32 v186, v97 offset:5360
	ds_write2st64_b32 v99, v61, v62 offset0:0 offset1:2
	s_waitcnt lgkmcnt(7)
	v_pk_mul_f32 v[58:59], v[52:53], v[32:33] op_sel_hi:[0,1]
	ds_read2_b64 v[232:235], v240 offset1:170
	v_add_u32_e32 v240, 0xaa0, v240
	ds_read_b128 v[194:197], v96 offset:5696
	ds_read_b128 v[198:201], v96 offset:5952
	v_pk_fma_f32 v[58:59], v[52:53], v[34:35], v[58:59] op_sel:[1,0,0]
	ds_read_b128 v[190:193], v96 offset:5440
	ds_read_b128 v[206:209], v96 offset:6464
	v_pk_fma_f32 v[58:59], v[48:49], v[36:37], v[58:59] op_sel_hi:[0,1,1]
	ds_read_b128 v[202:205], v96 offset:6208
	v_pk_fma_f32 v[58:59], v[48:49], v[38:39], v[58:59] op_sel:[1,0,0]
	v_pk_mul_f32 v[64:65], v[54:55], v[44:45] op_sel_hi:[0,1]
	v_pk_mul_f32 v[66:67], v[54:55], v[46:47] op_sel_hi:[0,1]
	v_add_f32_dpp v58, v58, v58 row_ror:8 row_mask:0xf bank_mask:0xf bound_ctrl:1
	v_pk_fma_f32 v[64:65], v[52:53], v[28:29], v[64:65]
	v_pk_fma_f32 v[66:67], v[48:49], v[30:31], v[66:67]
	v_add_f32_dpp v58, v58, v58 row_ror:4 row_mask:0xf bank_mask:0xf bound_ctrl:1
	v_add_f32_dpp v60, v59, v59 row_ror:8 row_mask:0xf bank_mask:0xf bound_ctrl:1
	s_nop 0
	v_add_f32_dpp v58, v58, v58 row_ror:2 row_mask:0xf bank_mask:0xf bound_ctrl:1
	v_fma_f32 v61, v54, v237, v60
	s_nop 0
	v_add_f32_dpp v58, v58, v58 row_ror:1 row_mask:0xf bank_mask:0xf bound_ctrl:1
	v_pk_fma_f32 v[52:53], v[58:59], v[40:41], v[64:65] op_sel_hi:[0,1,1]
	v_pk_fma_f32 v[48:49], v[58:59], v[42:43], v[66:67] op_sel_hi:[0,1,1]
	v_fma_f32 v61, v58, v236, v61
	ds_read_b32 v210, v97 offset:6720
	s_waitcnt lgkmcnt(8)
	v_pk_mul_f32 v[58:59], v[52:53], v[170:171] op_sel_hi:[0,1]
	ds_read_b128 v[32:35], v96 offset:7056
	ds_read_b128 v[36:39], v96 offset:7312
	v_pk_fma_f32 v[58:59], v[52:53], v[172:173], v[58:59] op_sel:[1,0,0]
	ds_read_b128 v[28:31], v96 offset:6800
	ds_read_b128 v[44:47], v96 offset:7824
	v_pk_fma_f32 v[58:59], v[48:49], v[174:175], v[58:59] op_sel_hi:[0,1,1]
	ds_read_b128 v[40:43], v96 offset:7568
	v_pk_fma_f32 v[58:59], v[48:49], v[176:177], v[58:59] op_sel:[1,0,0]
	v_pk_mul_f32 v[64:65], v[186:187], v[182:183] op_sel_hi:[0,1]
	v_pk_mul_f32 v[66:67], v[186:187], v[184:185] op_sel_hi:[0,1]
	v_add_f32_dpp v58, v58, v58 row_ror:8 row_mask:0xf bank_mask:0xf bound_ctrl:1
	v_pk_fma_f32 v[64:65], v[52:53], v[166:167], v[64:65]
	v_pk_fma_f32 v[66:67], v[48:49], v[168:169], v[66:67]
	v_add_f32_dpp v58, v58, v58 row_ror:4 row_mask:0xf bank_mask:0xf bound_ctrl:1
	v_add_f32_dpp v60, v59, v59 row_ror:8 row_mask:0xf bank_mask:0xf bound_ctrl:1
	s_nop 0
	v_add_f32_dpp v58, v58, v58 row_ror:2 row_mask:0xf bank_mask:0xf bound_ctrl:1
	v_fma_f32 v62, v186, v239, v60
	s_nop 0
	v_add_f32_dpp v58, v58, v58 row_ror:1 row_mask:0xf bank_mask:0xf bound_ctrl:1
	v_pk_fma_f32 v[52:53], v[58:59], v[178:179], v[64:65] op_sel_hi:[0,1,1]
	v_pk_fma_f32 v[48:49], v[58:59], v[180:181], v[66:67] op_sel_hi:[0,1,1]
	v_fma_f32 v62, v58, v238, v62
	ds_read_b32 v54, v97 offset:8080
	ds_write2st64_b32 v99, v61, v62 offset0:4 offset1:6
	s_waitcnt lgkmcnt(7)
	v_pk_mul_f32 v[58:59], v[52:53], v[194:195] op_sel_hi:[0,1]
	ds_read2_b64 v[236:239], v240 offset1:170
	v_add_u32_e32 v240, 0xaa0, v240
	ds_read_b128 v[170:173], v96 offset:8416
	ds_read_b128 v[174:177], v96 offset:8672
	v_pk_fma_f32 v[58:59], v[52:53], v[196:197], v[58:59] op_sel:[1,0,0]
	ds_read_b128 v[166:169], v96 offset:8160
	ds_read_b128 v[182:185], v96 offset:9184
	v_pk_fma_f32 v[58:59], v[48:49], v[198:199], v[58:59] op_sel_hi:[0,1,1]
	ds_read_b128 v[178:181], v96 offset:8928
	v_pk_fma_f32 v[58:59], v[48:49], v[200:201], v[58:59] op_sel:[1,0,0]
	v_pk_mul_f32 v[64:65], v[210:211], v[206:207] op_sel_hi:[0,1]
	v_pk_mul_f32 v[66:67], v[210:211], v[208:209] op_sel_hi:[0,1]
	v_add_f32_dpp v58, v58, v58 row_ror:8 row_mask:0xf bank_mask:0xf bound_ctrl:1
	v_pk_fma_f32 v[64:65], v[52:53], v[190:191], v[64:65]
	v_pk_fma_f32 v[66:67], v[48:49], v[192:193], v[66:67]
	v_add_f32_dpp v58, v58, v58 row_ror:4 row_mask:0xf bank_mask:0xf bound_ctrl:1
	v_add_f32_dpp v60, v59, v59 row_ror:8 row_mask:0xf bank_mask:0xf bound_ctrl:1
	s_nop 0
	v_add_f32_dpp v58, v58, v58 row_ror:2 row_mask:0xf bank_mask:0xf bound_ctrl:1
	v_fma_f32 v61, v210, v233, v60
	s_nop 0
	v_add_f32_dpp v58, v58, v58 row_ror:1 row_mask:0xf bank_mask:0xf bound_ctrl:1
	v_pk_fma_f32 v[52:53], v[58:59], v[202:203], v[64:65] op_sel_hi:[0,1,1]
	v_pk_fma_f32 v[48:49], v[58:59], v[204:205], v[66:67] op_sel_hi:[0,1,1]
	v_fma_f32 v61, v58, v232, v61
	ds_read_b32 v186, v97 offset:9440
	s_waitcnt lgkmcnt(8)
	v_pk_mul_f32 v[58:59], v[52:53], v[32:33] op_sel_hi:[0,1]
	ds_read_b128 v[194:197], v96 offset:9776
	ds_read_b128 v[198:201], v96 offset:10032
	v_pk_fma_f32 v[58:59], v[52:53], v[34:35], v[58:59] op_sel:[1,0,0]
	ds_read_b128 v[190:193], v96 offset:9520
	ds_read_b128 v[206:209], v96 offset:10544
	v_pk_fma_f32 v[58:59], v[48:49], v[36:37], v[58:59] op_sel_hi:[0,1,1]
	ds_read_b128 v[202:205], v96 offset:10288
	v_pk_fma_f32 v[58:59], v[48:49], v[38:39], v[58:59] op_sel:[1,0,0]
	v_pk_mul_f32 v[64:65], v[54:55], v[44:45] op_sel_hi:[0,1]
	v_pk_mul_f32 v[66:67], v[54:55], v[46:47] op_sel_hi:[0,1]
	v_add_f32_dpp v58, v58, v58 row_ror:8 row_mask:0xf bank_mask:0xf bound_ctrl:1
	v_pk_fma_f32 v[64:65], v[52:53], v[28:29], v[64:65]
	v_pk_fma_f32 v[66:67], v[48:49], v[30:31], v[66:67]
	v_add_f32_dpp v58, v58, v58 row_ror:4 row_mask:0xf bank_mask:0xf bound_ctrl:1
	v_add_f32_dpp v60, v59, v59 row_ror:8 row_mask:0xf bank_mask:0xf bound_ctrl:1
	s_nop 0
	v_add_f32_dpp v58, v58, v58 row_ror:2 row_mask:0xf bank_mask:0xf bound_ctrl:1
	v_fma_f32 v62, v54, v235, v60
	s_nop 0
	v_add_f32_dpp v58, v58, v58 row_ror:1 row_mask:0xf bank_mask:0xf bound_ctrl:1
	v_pk_fma_f32 v[52:53], v[58:59], v[40:41], v[64:65] op_sel_hi:[0,1,1]
	v_pk_fma_f32 v[48:49], v[58:59], v[42:43], v[66:67] op_sel_hi:[0,1,1]
	v_fma_f32 v62, v58, v234, v62
	ds_read_b32 v210, v97 offset:10800
	ds_write2st64_b32 v99, v61, v62 offset0:8 offset1:10
	s_waitcnt lgkmcnt(7)
	v_pk_mul_f32 v[58:59], v[52:53], v[170:171] op_sel_hi:[0,1]
	ds_read2_b64 v[232:235], v240 offset1:170
	v_add_u32_e32 v240, 0xaa0, v240
	ds_read_b128 v[32:35], v96 offset:11136
	ds_read_b128 v[36:39], v96 offset:11392
	v_pk_fma_f32 v[58:59], v[52:53], v[172:173], v[58:59] op_sel:[1,0,0]
	ds_read_b128 v[28:31], v96 offset:10880
	ds_read_b128 v[44:47], v96 offset:11904
	v_pk_fma_f32 v[58:59], v[48:49], v[174:175], v[58:59] op_sel_hi:[0,1,1]
	ds_read_b128 v[40:43], v96 offset:11648
	v_pk_fma_f32 v[58:59], v[48:49], v[176:177], v[58:59] op_sel:[1,0,0]
	v_pk_mul_f32 v[64:65], v[186:187], v[182:183] op_sel_hi:[0,1]
	v_pk_mul_f32 v[66:67], v[186:187], v[184:185] op_sel_hi:[0,1]
	v_add_f32_dpp v58, v58, v58 row_ror:8 row_mask:0xf bank_mask:0xf bound_ctrl:1
	v_pk_fma_f32 v[64:65], v[52:53], v[166:167], v[64:65]
	v_pk_fma_f32 v[66:67], v[48:49], v[168:169], v[66:67]
	v_add_f32_dpp v58, v58, v58 row_ror:4 row_mask:0xf bank_mask:0xf bound_ctrl:1
	v_add_f32_dpp v60, v59, v59 row_ror:8 row_mask:0xf bank_mask:0xf bound_ctrl:1
	s_nop 0
	v_add_f32_dpp v58, v58, v58 row_ror:2 row_mask:0xf bank_mask:0xf bound_ctrl:1
	v_fma_f32 v61, v186, v237, v60
	s_nop 0
	v_add_f32_dpp v58, v58, v58 row_ror:1 row_mask:0xf bank_mask:0xf bound_ctrl:1
	v_pk_fma_f32 v[52:53], v[58:59], v[178:179], v[64:65] op_sel_hi:[0,1,1]
	v_pk_fma_f32 v[48:49], v[58:59], v[180:181], v[66:67] op_sel_hi:[0,1,1]
	v_fma_f32 v61, v58, v236, v61
	ds_read_b32 v54, v97 offset:12160
	s_waitcnt lgkmcnt(8)
	v_pk_mul_f32 v[58:59], v[52:53], v[194:195] op_sel_hi:[0,1]
	ds_read_b128 v[170:173], v96 offset:12496
	ds_read_b128 v[174:177], v96 offset:12752
	v_pk_fma_f32 v[58:59], v[52:53], v[196:197], v[58:59] op_sel:[1,0,0]
	ds_read_b128 v[166:169], v96 offset:12240
	ds_read_b128 v[182:185], v96 offset:13264
	v_pk_fma_f32 v[58:59], v[48:49], v[198:199], v[58:59] op_sel_hi:[0,1,1]
	ds_read_b128 v[178:181], v96 offset:13008
	v_pk_fma_f32 v[58:59], v[48:49], v[200:201], v[58:59] op_sel:[1,0,0]
	v_pk_mul_f32 v[64:65], v[210:211], v[206:207] op_sel_hi:[0,1]
	v_pk_mul_f32 v[66:67], v[210:211], v[208:209] op_sel_hi:[0,1]
	v_add_f32_dpp v58, v58, v58 row_ror:8 row_mask:0xf bank_mask:0xf bound_ctrl:1
	v_pk_fma_f32 v[64:65], v[52:53], v[190:191], v[64:65]
	v_pk_fma_f32 v[66:67], v[48:49], v[192:193], v[66:67]
	v_add_f32_dpp v58, v58, v58 row_ror:4 row_mask:0xf bank_mask:0xf bound_ctrl:1
	v_add_f32_dpp v60, v59, v59 row_ror:8 row_mask:0xf bank_mask:0xf bound_ctrl:1
	s_nop 0
	v_add_f32_dpp v58, v58, v58 row_ror:2 row_mask:0xf bank_mask:0xf bound_ctrl:1
	v_fma_f32 v62, v210, v239, v60
	s_nop 0
	v_add_f32_dpp v58, v58, v58 row_ror:1 row_mask:0xf bank_mask:0xf bound_ctrl:1
	v_pk_fma_f32 v[52:53], v[58:59], v[202:203], v[64:65] op_sel_hi:[0,1,1]
	v_pk_fma_f32 v[48:49], v[58:59], v[204:205], v[66:67] op_sel_hi:[0,1,1]
	v_fma_f32 v62, v58, v238, v62
	ds_read_b32 v186, v97 offset:13520
	ds_write2st64_b32 v99, v61, v62 offset0:12 offset1:14
	s_waitcnt lgkmcnt(7)
	v_pk_mul_f32 v[58:59], v[52:53], v[32:33] op_sel_hi:[0,1]
	ds_read2_b64 v[236:239], v240 offset1:170
	v_add_u32_e32 v240, 0xaa0, v240
	ds_read_b128 v[194:197], v96 offset:13856
	ds_read_b128 v[198:201], v96 offset:14112
	v_pk_fma_f32 v[58:59], v[52:53], v[34:35], v[58:59] op_sel:[1,0,0]
	ds_read_b128 v[190:193], v96 offset:13600
	ds_read_b128 v[206:209], v96 offset:14624
	v_pk_fma_f32 v[58:59], v[48:49], v[36:37], v[58:59] op_sel_hi:[0,1,1]
	ds_read_b128 v[202:205], v96 offset:14368
	v_pk_fma_f32 v[58:59], v[48:49], v[38:39], v[58:59] op_sel:[1,0,0]
	v_pk_mul_f32 v[64:65], v[54:55], v[44:45] op_sel_hi:[0,1]
	v_pk_mul_f32 v[66:67], v[54:55], v[46:47] op_sel_hi:[0,1]
	v_add_f32_dpp v58, v58, v58 row_ror:8 row_mask:0xf bank_mask:0xf bound_ctrl:1
	v_pk_fma_f32 v[64:65], v[52:53], v[28:29], v[64:65]
	v_pk_fma_f32 v[66:67], v[48:49], v[30:31], v[66:67]
	v_add_f32_dpp v58, v58, v58 row_ror:4 row_mask:0xf bank_mask:0xf bound_ctrl:1
	v_add_f32_dpp v60, v59, v59 row_ror:8 row_mask:0xf bank_mask:0xf bound_ctrl:1
	s_nop 0
	v_add_f32_dpp v58, v58, v58 row_ror:2 row_mask:0xf bank_mask:0xf bound_ctrl:1
	v_fma_f32 v61, v54, v233, v60
	s_nop 0
	v_add_f32_dpp v58, v58, v58 row_ror:1 row_mask:0xf bank_mask:0xf bound_ctrl:1
	v_pk_fma_f32 v[52:53], v[58:59], v[40:41], v[64:65] op_sel_hi:[0,1,1]
	v_pk_fma_f32 v[48:49], v[58:59], v[42:43], v[66:67] op_sel_hi:[0,1,1]
	v_fma_f32 v61, v58, v232, v61
	ds_read_b32 v210, v97 offset:14880
	s_waitcnt lgkmcnt(8)
	v_pk_mul_f32 v[58:59], v[52:53], v[170:171] op_sel_hi:[0,1]
	ds_read_b128 v[32:35], v96 offset:15216
	ds_read_b128 v[36:39], v96 offset:15472
	v_pk_fma_f32 v[58:59], v[52:53], v[172:173], v[58:59] op_sel:[1,0,0]
	ds_read_b128 v[28:31], v96 offset:14960
	ds_read_b128 v[44:47], v96 offset:15984
	v_pk_fma_f32 v[58:59], v[48:49], v[174:175], v[58:59] op_sel_hi:[0,1,1]
	ds_read_b128 v[40:43], v96 offset:15728
	v_pk_fma_f32 v[58:59], v[48:49], v[176:177], v[58:59] op_sel:[1,0,0]
	v_pk_mul_f32 v[64:65], v[186:187], v[182:183] op_sel_hi:[0,1]
	v_pk_mul_f32 v[66:67], v[186:187], v[184:185] op_sel_hi:[0,1]
	v_add_f32_dpp v58, v58, v58 row_ror:8 row_mask:0xf bank_mask:0xf bound_ctrl:1
	v_pk_fma_f32 v[64:65], v[52:53], v[166:167], v[64:65]
	v_pk_fma_f32 v[66:67], v[48:49], v[168:169], v[66:67]
	v_add_f32_dpp v58, v58, v58 row_ror:4 row_mask:0xf bank_mask:0xf bound_ctrl:1
	v_add_f32_dpp v60, v59, v59 row_ror:8 row_mask:0xf bank_mask:0xf bound_ctrl:1
	s_nop 0
	v_add_f32_dpp v58, v58, v58 row_ror:2 row_mask:0xf bank_mask:0xf bound_ctrl:1
	v_fma_f32 v62, v186, v235, v60
	s_nop 0
	v_add_f32_dpp v58, v58, v58 row_ror:1 row_mask:0xf bank_mask:0xf bound_ctrl:1
	v_pk_fma_f32 v[52:53], v[58:59], v[178:179], v[64:65] op_sel_hi:[0,1,1]
	v_pk_fma_f32 v[48:49], v[58:59], v[180:181], v[66:67] op_sel_hi:[0,1,1]
	v_fma_f32 v62, v58, v234, v62
	ds_read_b32 v54, v97 offset:16240
	ds_write2st64_b32 v99, v61, v62 offset0:16 offset1:18
	s_waitcnt lgkmcnt(7)
	v_pk_mul_f32 v[58:59], v[52:53], v[194:195] op_sel_hi:[0,1]
	ds_read2_b64 v[232:235], v240 offset1:170
	v_add_u32_e32 v240, 0xaa0, v240
	ds_read_b128 v[170:173], v96 offset:16576
	ds_read_b128 v[174:177], v96 offset:16832
	v_pk_fma_f32 v[58:59], v[52:53], v[196:197], v[58:59] op_sel:[1,0,0]
	ds_read_b128 v[166:169], v96 offset:16320
	ds_read_b128 v[182:185], v96 offset:17344
	v_pk_fma_f32 v[58:59], v[48:49], v[198:199], v[58:59] op_sel_hi:[0,1,1]
	ds_read_b128 v[178:181], v96 offset:17088
	v_pk_fma_f32 v[58:59], v[48:49], v[200:201], v[58:59] op_sel:[1,0,0]
	v_pk_mul_f32 v[64:65], v[210:211], v[206:207] op_sel_hi:[0,1]
	v_pk_mul_f32 v[66:67], v[210:211], v[208:209] op_sel_hi:[0,1]
	v_add_f32_dpp v58, v58, v58 row_ror:8 row_mask:0xf bank_mask:0xf bound_ctrl:1
	v_pk_fma_f32 v[64:65], v[52:53], v[190:191], v[64:65]
	v_pk_fma_f32 v[66:67], v[48:49], v[192:193], v[66:67]
	v_add_f32_dpp v58, v58, v58 row_ror:4 row_mask:0xf bank_mask:0xf bound_ctrl:1
	v_add_f32_dpp v60, v59, v59 row_ror:8 row_mask:0xf bank_mask:0xf bound_ctrl:1
	s_nop 0
	v_add_f32_dpp v58, v58, v58 row_ror:2 row_mask:0xf bank_mask:0xf bound_ctrl:1
	v_fma_f32 v61, v210, v237, v60
	s_nop 0
	v_add_f32_dpp v58, v58, v58 row_ror:1 row_mask:0xf bank_mask:0xf bound_ctrl:1
	v_pk_fma_f32 v[52:53], v[58:59], v[202:203], v[64:65] op_sel_hi:[0,1,1]
	v_pk_fma_f32 v[48:49], v[58:59], v[204:205], v[66:67] op_sel_hi:[0,1,1]
	v_fma_f32 v61, v58, v236, v61
	ds_read_b32 v186, v97 offset:17600
	s_waitcnt lgkmcnt(8)
	v_pk_mul_f32 v[58:59], v[52:53], v[32:33] op_sel_hi:[0,1]
	ds_read_b128 v[194:197], v96 offset:17936
	ds_read_b128 v[198:201], v96 offset:18192
	v_pk_fma_f32 v[58:59], v[52:53], v[34:35], v[58:59] op_sel:[1,0,0]
	ds_read_b128 v[190:193], v96 offset:17680
	ds_read_b128 v[206:209], v96 offset:18704
	v_pk_fma_f32 v[58:59], v[48:49], v[36:37], v[58:59] op_sel_hi:[0,1,1]
	ds_read_b128 v[202:205], v96 offset:18448
	v_pk_fma_f32 v[58:59], v[48:49], v[38:39], v[58:59] op_sel:[1,0,0]
	v_pk_mul_f32 v[64:65], v[54:55], v[44:45] op_sel_hi:[0,1]
	v_pk_mul_f32 v[66:67], v[54:55], v[46:47] op_sel_hi:[0,1]
	v_add_f32_dpp v58, v58, v58 row_ror:8 row_mask:0xf bank_mask:0xf bound_ctrl:1
	v_pk_fma_f32 v[64:65], v[52:53], v[28:29], v[64:65]
	v_pk_fma_f32 v[66:67], v[48:49], v[30:31], v[66:67]
	v_add_f32_dpp v58, v58, v58 row_ror:4 row_mask:0xf bank_mask:0xf bound_ctrl:1
	v_add_f32_dpp v60, v59, v59 row_ror:8 row_mask:0xf bank_mask:0xf bound_ctrl:1
	s_nop 0
	v_add_f32_dpp v58, v58, v58 row_ror:2 row_mask:0xf bank_mask:0xf bound_ctrl:1
	v_fma_f32 v62, v54, v239, v60
	s_nop 0
	v_add_f32_dpp v58, v58, v58 row_ror:1 row_mask:0xf bank_mask:0xf bound_ctrl:1
	v_pk_fma_f32 v[52:53], v[58:59], v[40:41], v[64:65] op_sel_hi:[0,1,1]
	v_pk_fma_f32 v[48:49], v[58:59], v[42:43], v[66:67] op_sel_hi:[0,1,1]
	v_fma_f32 v62, v58, v238, v62
	ds_read_b32 v210, v97 offset:18960
	ds_write2st64_b32 v99, v61, v62 offset0:20 offset1:22
	s_waitcnt lgkmcnt(7)
	v_pk_mul_f32 v[58:59], v[52:53], v[170:171] op_sel_hi:[0,1]
	ds_read2_b64 v[236:239], v240 offset1:170
	v_add_u32_e32 v240, 0xaa0, v240
	ds_read_b128 v[32:35], v96 offset:19296
	ds_read_b128 v[36:39], v96 offset:19552
	v_pk_fma_f32 v[58:59], v[52:53], v[172:173], v[58:59] op_sel:[1,0,0]
	ds_read_b128 v[28:31], v96 offset:19040
	ds_read_b128 v[44:47], v96 offset:20064
	v_pk_fma_f32 v[58:59], v[48:49], v[174:175], v[58:59] op_sel_hi:[0,1,1]
	ds_read_b128 v[40:43], v96 offset:19808
	v_pk_fma_f32 v[58:59], v[48:49], v[176:177], v[58:59] op_sel:[1,0,0]
	v_pk_mul_f32 v[64:65], v[186:187], v[182:183] op_sel_hi:[0,1]
	v_pk_mul_f32 v[66:67], v[186:187], v[184:185] op_sel_hi:[0,1]
	v_add_f32_dpp v58, v58, v58 row_ror:8 row_mask:0xf bank_mask:0xf bound_ctrl:1
	v_pk_fma_f32 v[64:65], v[52:53], v[166:167], v[64:65]
	v_pk_fma_f32 v[66:67], v[48:49], v[168:169], v[66:67]
	v_add_f32_dpp v58, v58, v58 row_ror:4 row_mask:0xf bank_mask:0xf bound_ctrl:1
	v_add_f32_dpp v60, v59, v59 row_ror:8 row_mask:0xf bank_mask:0xf bound_ctrl:1
	s_nop 0
	v_add_f32_dpp v58, v58, v58 row_ror:2 row_mask:0xf bank_mask:0xf bound_ctrl:1
	v_fma_f32 v61, v186, v233, v60
	s_nop 0
	v_add_f32_dpp v58, v58, v58 row_ror:1 row_mask:0xf bank_mask:0xf bound_ctrl:1
	v_pk_fma_f32 v[52:53], v[58:59], v[178:179], v[64:65] op_sel_hi:[0,1,1]
	v_pk_fma_f32 v[48:49], v[58:59], v[180:181], v[66:67] op_sel_hi:[0,1,1]
	v_fma_f32 v61, v58, v232, v61
	ds_read_b32 v54, v97 offset:20320
	s_waitcnt lgkmcnt(8)
	v_pk_mul_f32 v[58:59], v[52:53], v[194:195] op_sel_hi:[0,1]
	ds_read_b128 v[170:173], v96 offset:20656
	ds_read_b128 v[174:177], v96 offset:20912
	v_pk_fma_f32 v[58:59], v[52:53], v[196:197], v[58:59] op_sel:[1,0,0]
	ds_read_b128 v[166:169], v96 offset:20400
	ds_read_b128 v[182:185], v96 offset:21424
	v_pk_fma_f32 v[58:59], v[48:49], v[198:199], v[58:59] op_sel_hi:[0,1,1]
	ds_read_b128 v[178:181], v96 offset:21168
	v_pk_fma_f32 v[58:59], v[48:49], v[200:201], v[58:59] op_sel:[1,0,0]
	v_pk_mul_f32 v[64:65], v[210:211], v[206:207] op_sel_hi:[0,1]
	v_pk_mul_f32 v[66:67], v[210:211], v[208:209] op_sel_hi:[0,1]
	v_add_f32_dpp v58, v58, v58 row_ror:8 row_mask:0xf bank_mask:0xf bound_ctrl:1
	v_pk_fma_f32 v[64:65], v[52:53], v[190:191], v[64:65]
	v_pk_fma_f32 v[66:67], v[48:49], v[192:193], v[66:67]
	v_add_f32_dpp v58, v58, v58 row_ror:4 row_mask:0xf bank_mask:0xf bound_ctrl:1
	v_add_f32_dpp v60, v59, v59 row_ror:8 row_mask:0xf bank_mask:0xf bound_ctrl:1
	s_nop 0
	v_add_f32_dpp v58, v58, v58 row_ror:2 row_mask:0xf bank_mask:0xf bound_ctrl:1
	v_fma_f32 v62, v210, v235, v60
	s_nop 0
	v_add_f32_dpp v58, v58, v58 row_ror:1 row_mask:0xf bank_mask:0xf bound_ctrl:1
	v_pk_fma_f32 v[52:53], v[58:59], v[202:203], v[64:65] op_sel_hi:[0,1,1]
	v_pk_fma_f32 v[48:49], v[58:59], v[204:205], v[66:67] op_sel_hi:[0,1,1]
	v_fma_f32 v62, v58, v234, v62
	ds_read_b32 v186, v97 offset:21680
	ds_write2st64_b32 v99, v61, v62 offset0:24 offset1:26
	s_waitcnt lgkmcnt(7)
	v_pk_mul_f32 v[58:59], v[52:53], v[32:33] op_sel_hi:[0,1]
	ds_read2_b64 v[232:235], v240 offset1:170
	v_add_u32_e32 v240, 0xaa0, v240
	ds_read_b128 v[194:197], v96 offset:22016
	ds_read_b128 v[198:201], v96 offset:22272
	v_pk_fma_f32 v[58:59], v[52:53], v[34:35], v[58:59] op_sel:[1,0,0]
	ds_read_b128 v[190:193], v96 offset:21760
	ds_read_b128 v[206:209], v96 offset:22784
	v_pk_fma_f32 v[58:59], v[48:49], v[36:37], v[58:59] op_sel_hi:[0,1,1]
	ds_read_b128 v[202:205], v96 offset:22528
	v_pk_fma_f32 v[58:59], v[48:49], v[38:39], v[58:59] op_sel:[1,0,0]
	v_pk_mul_f32 v[64:65], v[54:55], v[44:45] op_sel_hi:[0,1]
	v_pk_mul_f32 v[66:67], v[54:55], v[46:47] op_sel_hi:[0,1]
	v_add_f32_dpp v58, v58, v58 row_ror:8 row_mask:0xf bank_mask:0xf bound_ctrl:1
	v_pk_fma_f32 v[64:65], v[52:53], v[28:29], v[64:65]
	v_pk_fma_f32 v[66:67], v[48:49], v[30:31], v[66:67]
	v_add_f32_dpp v58, v58, v58 row_ror:4 row_mask:0xf bank_mask:0xf bound_ctrl:1
	v_add_f32_dpp v60, v59, v59 row_ror:8 row_mask:0xf bank_mask:0xf bound_ctrl:1
	s_nop 0
	v_add_f32_dpp v58, v58, v58 row_ror:2 row_mask:0xf bank_mask:0xf bound_ctrl:1
	v_fma_f32 v61, v54, v237, v60
	s_nop 0
	v_add_f32_dpp v58, v58, v58 row_ror:1 row_mask:0xf bank_mask:0xf bound_ctrl:1
	v_pk_fma_f32 v[52:53], v[58:59], v[40:41], v[64:65] op_sel_hi:[0,1,1]
	v_pk_fma_f32 v[48:49], v[58:59], v[42:43], v[66:67] op_sel_hi:[0,1,1]
	v_fma_f32 v61, v58, v236, v61
	ds_read_b32 v210, v97 offset:23040
	s_waitcnt lgkmcnt(8)
	v_pk_mul_f32 v[58:59], v[52:53], v[170:171] op_sel_hi:[0,1]
	ds_read_b128 v[32:35], v96 offset:23376
	ds_read_b128 v[36:39], v96 offset:23632
	v_pk_fma_f32 v[58:59], v[52:53], v[172:173], v[58:59] op_sel:[1,0,0]
	ds_read_b128 v[28:31], v96 offset:23120
	ds_read_b128 v[44:47], v96 offset:24144
	v_pk_fma_f32 v[58:59], v[48:49], v[174:175], v[58:59] op_sel_hi:[0,1,1]
	ds_read_b128 v[40:43], v96 offset:23888
	v_pk_fma_f32 v[58:59], v[48:49], v[176:177], v[58:59] op_sel:[1,0,0]
	v_pk_mul_f32 v[64:65], v[186:187], v[182:183] op_sel_hi:[0,1]
	v_pk_mul_f32 v[66:67], v[186:187], v[184:185] op_sel_hi:[0,1]
	v_add_f32_dpp v58, v58, v58 row_ror:8 row_mask:0xf bank_mask:0xf bound_ctrl:1
	v_pk_fma_f32 v[64:65], v[52:53], v[166:167], v[64:65]
	v_pk_fma_f32 v[66:67], v[48:49], v[168:169], v[66:67]
	v_add_f32_dpp v58, v58, v58 row_ror:4 row_mask:0xf bank_mask:0xf bound_ctrl:1
	v_add_f32_dpp v60, v59, v59 row_ror:8 row_mask:0xf bank_mask:0xf bound_ctrl:1
	s_nop 0
	v_add_f32_dpp v58, v58, v58 row_ror:2 row_mask:0xf bank_mask:0xf bound_ctrl:1
	v_fma_f32 v62, v186, v239, v60
	s_nop 0
	v_add_f32_dpp v58, v58, v58 row_ror:1 row_mask:0xf bank_mask:0xf bound_ctrl:1
	v_pk_fma_f32 v[52:53], v[58:59], v[178:179], v[64:65] op_sel_hi:[0,1,1]
	v_pk_fma_f32 v[48:49], v[58:59], v[180:181], v[66:67] op_sel_hi:[0,1,1]
	v_fma_f32 v62, v58, v238, v62
	ds_read_b32 v54, v97 offset:24400
	ds_write2st64_b32 v99, v61, v62 offset0:28 offset1:30
	s_waitcnt lgkmcnt(7)
	v_pk_mul_f32 v[58:59], v[52:53], v[194:195] op_sel_hi:[0,1]
	ds_read2_b64 v[236:239], v240 offset1:170
	v_add_u32_e32 v240, 0xaa0, v240
	ds_read_b128 v[170:173], v96 offset:24736
	ds_read_b128 v[174:177], v96 offset:24992
	v_pk_fma_f32 v[58:59], v[52:53], v[196:197], v[58:59] op_sel:[1,0,0]
	ds_read_b128 v[166:169], v96 offset:24480
	ds_read_b128 v[182:185], v96 offset:25504
	v_pk_fma_f32 v[58:59], v[48:49], v[198:199], v[58:59] op_sel_hi:[0,1,1]
	ds_read_b128 v[178:181], v96 offset:25248
	v_pk_fma_f32 v[58:59], v[48:49], v[200:201], v[58:59] op_sel:[1,0,0]
	v_pk_mul_f32 v[64:65], v[210:211], v[206:207] op_sel_hi:[0,1]
	v_pk_mul_f32 v[66:67], v[210:211], v[208:209] op_sel_hi:[0,1]
	v_add_f32_dpp v58, v58, v58 row_ror:8 row_mask:0xf bank_mask:0xf bound_ctrl:1
	v_pk_fma_f32 v[64:65], v[52:53], v[190:191], v[64:65]
	v_pk_fma_f32 v[66:67], v[48:49], v[192:193], v[66:67]
	v_add_f32_dpp v58, v58, v58 row_ror:4 row_mask:0xf bank_mask:0xf bound_ctrl:1
	v_add_f32_dpp v60, v59, v59 row_ror:8 row_mask:0xf bank_mask:0xf bound_ctrl:1
	s_nop 0
	v_add_f32_dpp v58, v58, v58 row_ror:2 row_mask:0xf bank_mask:0xf bound_ctrl:1
	v_fma_f32 v61, v210, v233, v60
	s_nop 0
	v_add_f32_dpp v58, v58, v58 row_ror:1 row_mask:0xf bank_mask:0xf bound_ctrl:1
	v_pk_fma_f32 v[52:53], v[58:59], v[202:203], v[64:65] op_sel_hi:[0,1,1]
	v_pk_fma_f32 v[48:49], v[58:59], v[204:205], v[66:67] op_sel_hi:[0,1,1]
	v_fma_f32 v61, v58, v232, v61
	ds_read_b32 v186, v97 offset:25760
	s_waitcnt lgkmcnt(8)
	v_pk_mul_f32 v[58:59], v[52:53], v[32:33] op_sel_hi:[0,1]
	ds_read_b128 v[194:197], v96 offset:26096
	ds_read_b128 v[198:201], v96 offset:26352
	v_pk_fma_f32 v[58:59], v[52:53], v[34:35], v[58:59] op_sel:[1,0,0]
	ds_read_b128 v[190:193], v96 offset:25840
	ds_read_b128 v[206:209], v96 offset:26864
	v_pk_fma_f32 v[58:59], v[48:49], v[36:37], v[58:59] op_sel_hi:[0,1,1]
	ds_read_b128 v[202:205], v96 offset:26608
	v_pk_fma_f32 v[58:59], v[48:49], v[38:39], v[58:59] op_sel:[1,0,0]
	v_pk_mul_f32 v[64:65], v[54:55], v[44:45] op_sel_hi:[0,1]
	v_pk_mul_f32 v[66:67], v[54:55], v[46:47] op_sel_hi:[0,1]
	v_add_f32_dpp v58, v58, v58 row_ror:8 row_mask:0xf bank_mask:0xf bound_ctrl:1
	v_pk_fma_f32 v[64:65], v[52:53], v[28:29], v[64:65]
	v_pk_fma_f32 v[66:67], v[48:49], v[30:31], v[66:67]
	v_add_f32_dpp v58, v58, v58 row_ror:4 row_mask:0xf bank_mask:0xf bound_ctrl:1
	v_add_f32_dpp v60, v59, v59 row_ror:8 row_mask:0xf bank_mask:0xf bound_ctrl:1
	s_nop 0
	v_add_f32_dpp v58, v58, v58 row_ror:2 row_mask:0xf bank_mask:0xf bound_ctrl:1
	v_fma_f32 v62, v54, v235, v60
	s_nop 0
	v_add_f32_dpp v58, v58, v58 row_ror:1 row_mask:0xf bank_mask:0xf bound_ctrl:1
	v_pk_fma_f32 v[52:53], v[58:59], v[40:41], v[64:65] op_sel_hi:[0,1,1]
	v_pk_fma_f32 v[48:49], v[58:59], v[42:43], v[66:67] op_sel_hi:[0,1,1]
	v_fma_f32 v62, v58, v234, v62
	ds_read_b32 v210, v97 offset:27120
	ds_write2st64_b32 v99, v61, v62 offset0:32 offset1:34
	s_waitcnt lgkmcnt(7)
	v_pk_mul_f32 v[58:59], v[52:53], v[170:171] op_sel_hi:[0,1]
	ds_read2_b64 v[232:235], v240 offset1:170
	v_add_u32_e32 v240, 0xaa0, v240
	ds_read_b128 v[32:35], v96 offset:27456
	ds_read_b128 v[36:39], v96 offset:27712
	v_pk_fma_f32 v[58:59], v[52:53], v[172:173], v[58:59] op_sel:[1,0,0]
	ds_read_b128 v[28:31], v96 offset:27200
	ds_read_b128 v[44:47], v96 offset:28224
	v_pk_fma_f32 v[58:59], v[48:49], v[174:175], v[58:59] op_sel_hi:[0,1,1]
	ds_read_b128 v[40:43], v96 offset:27968
	v_pk_fma_f32 v[58:59], v[48:49], v[176:177], v[58:59] op_sel:[1,0,0]
	v_pk_mul_f32 v[64:65], v[186:187], v[182:183] op_sel_hi:[0,1]
	v_pk_mul_f32 v[66:67], v[186:187], v[184:185] op_sel_hi:[0,1]
	v_add_f32_dpp v58, v58, v58 row_ror:8 row_mask:0xf bank_mask:0xf bound_ctrl:1
	v_pk_fma_f32 v[64:65], v[52:53], v[166:167], v[64:65]
	v_pk_fma_f32 v[66:67], v[48:49], v[168:169], v[66:67]
	v_add_f32_dpp v58, v58, v58 row_ror:4 row_mask:0xf bank_mask:0xf bound_ctrl:1
	v_add_f32_dpp v60, v59, v59 row_ror:8 row_mask:0xf bank_mask:0xf bound_ctrl:1
	s_nop 0
	v_add_f32_dpp v58, v58, v58 row_ror:2 row_mask:0xf bank_mask:0xf bound_ctrl:1
	v_fma_f32 v61, v186, v237, v60
	s_nop 0
	v_add_f32_dpp v58, v58, v58 row_ror:1 row_mask:0xf bank_mask:0xf bound_ctrl:1
	v_pk_fma_f32 v[52:53], v[58:59], v[178:179], v[64:65] op_sel_hi:[0,1,1]
	v_pk_fma_f32 v[48:49], v[58:59], v[180:181], v[66:67] op_sel_hi:[0,1,1]
	v_fma_f32 v61, v58, v236, v61
	ds_read_b32 v54, v97 offset:28480
	s_waitcnt lgkmcnt(8)
	v_pk_mul_f32 v[58:59], v[52:53], v[194:195] op_sel_hi:[0,1]
	ds_read_b128 v[170:173], v96 offset:28816
	ds_read_b128 v[174:177], v96 offset:29072
	v_pk_fma_f32 v[58:59], v[52:53], v[196:197], v[58:59] op_sel:[1,0,0]
	ds_read_b128 v[166:169], v96 offset:28560
	ds_read_b128 v[182:185], v96 offset:29584
	v_pk_fma_f32 v[58:59], v[48:49], v[198:199], v[58:59] op_sel_hi:[0,1,1]
	ds_read_b128 v[178:181], v96 offset:29328
	v_pk_fma_f32 v[58:59], v[48:49], v[200:201], v[58:59] op_sel:[1,0,0]
	v_pk_mul_f32 v[64:65], v[210:211], v[206:207] op_sel_hi:[0,1]
	v_pk_mul_f32 v[66:67], v[210:211], v[208:209] op_sel_hi:[0,1]
	v_add_f32_dpp v58, v58, v58 row_ror:8 row_mask:0xf bank_mask:0xf bound_ctrl:1
	v_pk_fma_f32 v[64:65], v[52:53], v[190:191], v[64:65]
	v_pk_fma_f32 v[66:67], v[48:49], v[192:193], v[66:67]
	v_add_f32_dpp v58, v58, v58 row_ror:4 row_mask:0xf bank_mask:0xf bound_ctrl:1
	v_add_f32_dpp v60, v59, v59 row_ror:8 row_mask:0xf bank_mask:0xf bound_ctrl:1
	s_nop 0
	v_add_f32_dpp v58, v58, v58 row_ror:2 row_mask:0xf bank_mask:0xf bound_ctrl:1
	v_fma_f32 v62, v210, v239, v60
	s_nop 0
	v_add_f32_dpp v58, v58, v58 row_ror:1 row_mask:0xf bank_mask:0xf bound_ctrl:1
	v_pk_fma_f32 v[52:53], v[58:59], v[202:203], v[64:65] op_sel_hi:[0,1,1]
	v_pk_fma_f32 v[48:49], v[58:59], v[204:205], v[66:67] op_sel_hi:[0,1,1]
	v_fma_f32 v62, v58, v238, v62
	ds_read_b32 v186, v97 offset:29840
	ds_write2st64_b32 v99, v61, v62 offset0:36 offset1:38
	s_waitcnt lgkmcnt(7)
	v_pk_mul_f32 v[58:59], v[52:53], v[32:33] op_sel_hi:[0,1]
	ds_read2_b64 v[236:239], v240 offset1:170
	v_add_u32_e32 v240, 0xaa0, v240
	ds_read_b128 v[194:197], v96 offset:30176
	ds_read_b128 v[198:201], v96 offset:30432
	v_pk_fma_f32 v[58:59], v[52:53], v[34:35], v[58:59] op_sel:[1,0,0]
	ds_read_b128 v[190:193], v96 offset:29920
	ds_read_b128 v[206:209], v96 offset:30944
	v_pk_fma_f32 v[58:59], v[48:49], v[36:37], v[58:59] op_sel_hi:[0,1,1]
	ds_read_b128 v[202:205], v96 offset:30688
	v_pk_fma_f32 v[58:59], v[48:49], v[38:39], v[58:59] op_sel:[1,0,0]
	v_pk_mul_f32 v[64:65], v[54:55], v[44:45] op_sel_hi:[0,1]
	v_pk_mul_f32 v[66:67], v[54:55], v[46:47] op_sel_hi:[0,1]
	v_add_f32_dpp v58, v58, v58 row_ror:8 row_mask:0xf bank_mask:0xf bound_ctrl:1
	v_pk_fma_f32 v[64:65], v[52:53], v[28:29], v[64:65]
	v_pk_fma_f32 v[66:67], v[48:49], v[30:31], v[66:67]
	v_add_f32_dpp v58, v58, v58 row_ror:4 row_mask:0xf bank_mask:0xf bound_ctrl:1
	v_add_f32_dpp v60, v59, v59 row_ror:8 row_mask:0xf bank_mask:0xf bound_ctrl:1
	s_nop 0
	v_add_f32_dpp v58, v58, v58 row_ror:2 row_mask:0xf bank_mask:0xf bound_ctrl:1
	v_fma_f32 v61, v54, v233, v60
	s_nop 0
	v_add_f32_dpp v58, v58, v58 row_ror:1 row_mask:0xf bank_mask:0xf bound_ctrl:1
	v_pk_fma_f32 v[52:53], v[58:59], v[40:41], v[64:65] op_sel_hi:[0,1,1]
	v_pk_fma_f32 v[48:49], v[58:59], v[42:43], v[66:67] op_sel_hi:[0,1,1]
	v_fma_f32 v61, v58, v232, v61
	ds_read_b32 v210, v97 offset:31200
	s_waitcnt lgkmcnt(8)
	v_pk_mul_f32 v[58:59], v[52:53], v[170:171] op_sel_hi:[0,1]
	ds_read_b128 v[32:35], v96 offset:31536
	ds_read_b128 v[36:39], v96 offset:31792
	v_pk_fma_f32 v[58:59], v[52:53], v[172:173], v[58:59] op_sel:[1,0,0]
	ds_read_b128 v[28:31], v96 offset:31280
	ds_read_b128 v[44:47], v96 offset:32304
	v_pk_fma_f32 v[58:59], v[48:49], v[174:175], v[58:59] op_sel_hi:[0,1,1]
	ds_read_b128 v[40:43], v96 offset:32048
	v_pk_fma_f32 v[58:59], v[48:49], v[176:177], v[58:59] op_sel:[1,0,0]
	v_pk_mul_f32 v[64:65], v[186:187], v[182:183] op_sel_hi:[0,1]
	v_pk_mul_f32 v[66:67], v[186:187], v[184:185] op_sel_hi:[0,1]
	v_add_f32_dpp v58, v58, v58 row_ror:8 row_mask:0xf bank_mask:0xf bound_ctrl:1
	v_pk_fma_f32 v[64:65], v[52:53], v[166:167], v[64:65]
	v_pk_fma_f32 v[66:67], v[48:49], v[168:169], v[66:67]
	v_add_f32_dpp v58, v58, v58 row_ror:4 row_mask:0xf bank_mask:0xf bound_ctrl:1
	v_add_f32_dpp v60, v59, v59 row_ror:8 row_mask:0xf bank_mask:0xf bound_ctrl:1
	s_nop 0
	v_add_f32_dpp v58, v58, v58 row_ror:2 row_mask:0xf bank_mask:0xf bound_ctrl:1
	v_fma_f32 v62, v186, v235, v60
	s_nop 0
	v_add_f32_dpp v58, v58, v58 row_ror:1 row_mask:0xf bank_mask:0xf bound_ctrl:1
	v_pk_fma_f32 v[52:53], v[58:59], v[178:179], v[64:65] op_sel_hi:[0,1,1]
	v_pk_fma_f32 v[48:49], v[58:59], v[180:181], v[66:67] op_sel_hi:[0,1,1]
	v_fma_f32 v62, v58, v234, v62
	ds_read_b32 v54, v97 offset:32560
	ds_write2st64_b32 v99, v61, v62 offset0:40 offset1:42
	s_waitcnt lgkmcnt(7)
	v_pk_mul_f32 v[58:59], v[52:53], v[194:195] op_sel_hi:[0,1]
	ds_read2_b64 v[232:235], v240 offset1:170
	v_add_u32_e32 v240, 0xaa0, v240
	ds_read_b128 v[170:173], v96 offset:32896
	ds_read_b128 v[174:177], v96 offset:33152
	v_pk_fma_f32 v[58:59], v[52:53], v[196:197], v[58:59] op_sel:[1,0,0]
	ds_read_b128 v[166:169], v96 offset:32640
	ds_read_b128 v[182:185], v96 offset:33664
	v_pk_fma_f32 v[58:59], v[48:49], v[198:199], v[58:59] op_sel_hi:[0,1,1]
	ds_read_b128 v[178:181], v96 offset:33408
	v_pk_fma_f32 v[58:59], v[48:49], v[200:201], v[58:59] op_sel:[1,0,0]
	v_pk_mul_f32 v[64:65], v[210:211], v[206:207] op_sel_hi:[0,1]
	v_pk_mul_f32 v[66:67], v[210:211], v[208:209] op_sel_hi:[0,1]
	v_add_f32_dpp v58, v58, v58 row_ror:8 row_mask:0xf bank_mask:0xf bound_ctrl:1
	v_pk_fma_f32 v[64:65], v[52:53], v[190:191], v[64:65]
	v_pk_fma_f32 v[66:67], v[48:49], v[192:193], v[66:67]
	v_add_f32_dpp v58, v58, v58 row_ror:4 row_mask:0xf bank_mask:0xf bound_ctrl:1
	v_add_f32_dpp v60, v59, v59 row_ror:8 row_mask:0xf bank_mask:0xf bound_ctrl:1
	s_nop 0
	v_add_f32_dpp v58, v58, v58 row_ror:2 row_mask:0xf bank_mask:0xf bound_ctrl:1
	v_fma_f32 v61, v210, v237, v60
	s_nop 0
	v_add_f32_dpp v58, v58, v58 row_ror:1 row_mask:0xf bank_mask:0xf bound_ctrl:1
	v_pk_fma_f32 v[52:53], v[58:59], v[202:203], v[64:65] op_sel_hi:[0,1,1]
	v_pk_fma_f32 v[48:49], v[58:59], v[204:205], v[66:67] op_sel_hi:[0,1,1]
	v_fma_f32 v61, v58, v236, v61
	ds_read_b32 v186, v97 offset:33920
	s_waitcnt lgkmcnt(8)
	v_pk_mul_f32 v[58:59], v[52:53], v[32:33] op_sel_hi:[0,1]
	ds_read_b128 v[194:197], v96 offset:34256
	ds_read_b128 v[198:201], v96 offset:34512
	v_pk_fma_f32 v[58:59], v[52:53], v[34:35], v[58:59] op_sel:[1,0,0]
	ds_read_b128 v[190:193], v96 offset:34000
	ds_read_b128 v[206:209], v96 offset:35024
	v_pk_fma_f32 v[58:59], v[48:49], v[36:37], v[58:59] op_sel_hi:[0,1,1]
	ds_read_b128 v[202:205], v96 offset:34768
	v_pk_fma_f32 v[58:59], v[48:49], v[38:39], v[58:59] op_sel:[1,0,0]
	v_pk_mul_f32 v[64:65], v[54:55], v[44:45] op_sel_hi:[0,1]
	v_pk_mul_f32 v[66:67], v[54:55], v[46:47] op_sel_hi:[0,1]
	v_add_f32_dpp v58, v58, v58 row_ror:8 row_mask:0xf bank_mask:0xf bound_ctrl:1
	v_pk_fma_f32 v[64:65], v[52:53], v[28:29], v[64:65]
	v_pk_fma_f32 v[66:67], v[48:49], v[30:31], v[66:67]
	v_add_f32_dpp v58, v58, v58 row_ror:4 row_mask:0xf bank_mask:0xf bound_ctrl:1
	v_add_f32_dpp v60, v59, v59 row_ror:8 row_mask:0xf bank_mask:0xf bound_ctrl:1
	s_nop 0
	v_add_f32_dpp v58, v58, v58 row_ror:2 row_mask:0xf bank_mask:0xf bound_ctrl:1
	v_fma_f32 v62, v54, v239, v60
	s_nop 0
	v_add_f32_dpp v58, v58, v58 row_ror:1 row_mask:0xf bank_mask:0xf bound_ctrl:1
	v_pk_fma_f32 v[52:53], v[58:59], v[40:41], v[64:65] op_sel_hi:[0,1,1]
	v_pk_fma_f32 v[48:49], v[58:59], v[42:43], v[66:67] op_sel_hi:[0,1,1]
	v_fma_f32 v62, v58, v238, v62
	ds_read_b32 v210, v97 offset:35280
	ds_write2st64_b32 v99, v61, v62 offset0:44 offset1:46
	s_waitcnt lgkmcnt(7)
	v_pk_mul_f32 v[58:59], v[52:53], v[170:171] op_sel_hi:[0,1]
	ds_read2_b64 v[236:239], v240 offset1:170
	v_add_u32_e32 v240, 0xaa0, v240
	ds_read_b128 v[32:35], v96 offset:35616
	ds_read_b128 v[36:39], v96 offset:35872
	v_pk_fma_f32 v[58:59], v[52:53], v[172:173], v[58:59] op_sel:[1,0,0]
	ds_read_b128 v[28:31], v96 offset:35360
	ds_read_b128 v[44:47], v96 offset:36384
	v_pk_fma_f32 v[58:59], v[48:49], v[174:175], v[58:59] op_sel_hi:[0,1,1]
	ds_read_b128 v[40:43], v96 offset:36128
	v_pk_fma_f32 v[58:59], v[48:49], v[176:177], v[58:59] op_sel:[1,0,0]
	v_pk_mul_f32 v[64:65], v[186:187], v[182:183] op_sel_hi:[0,1]
	v_pk_mul_f32 v[66:67], v[186:187], v[184:185] op_sel_hi:[0,1]
	v_add_f32_dpp v58, v58, v58 row_ror:8 row_mask:0xf bank_mask:0xf bound_ctrl:1
	v_pk_fma_f32 v[64:65], v[52:53], v[166:167], v[64:65]
	v_pk_fma_f32 v[66:67], v[48:49], v[168:169], v[66:67]
	v_add_f32_dpp v58, v58, v58 row_ror:4 row_mask:0xf bank_mask:0xf bound_ctrl:1
	v_add_f32_dpp v60, v59, v59 row_ror:8 row_mask:0xf bank_mask:0xf bound_ctrl:1
	s_nop 0
	v_add_f32_dpp v58, v58, v58 row_ror:2 row_mask:0xf bank_mask:0xf bound_ctrl:1
	v_fma_f32 v61, v186, v233, v60
	s_nop 0
	v_add_f32_dpp v58, v58, v58 row_ror:1 row_mask:0xf bank_mask:0xf bound_ctrl:1
	v_pk_fma_f32 v[52:53], v[58:59], v[178:179], v[64:65] op_sel_hi:[0,1,1]
	v_pk_fma_f32 v[48:49], v[58:59], v[180:181], v[66:67] op_sel_hi:[0,1,1]
	v_fma_f32 v61, v58, v232, v61
	ds_read_b32 v54, v97 offset:36640
	s_waitcnt lgkmcnt(8)
	v_pk_mul_f32 v[58:59], v[52:53], v[194:195] op_sel_hi:[0,1]
	ds_read_b128 v[170:173], v96 offset:36976
	ds_read_b128 v[174:177], v96 offset:37232
	v_pk_fma_f32 v[58:59], v[52:53], v[196:197], v[58:59] op_sel:[1,0,0]
	ds_read_b128 v[166:169], v96 offset:36720
	ds_read_b128 v[182:185], v96 offset:37744
	v_pk_fma_f32 v[58:59], v[48:49], v[198:199], v[58:59] op_sel_hi:[0,1,1]
	ds_read_b128 v[178:181], v96 offset:37488
	v_pk_fma_f32 v[58:59], v[48:49], v[200:201], v[58:59] op_sel:[1,0,0]
	v_pk_mul_f32 v[64:65], v[210:211], v[206:207] op_sel_hi:[0,1]
	v_pk_mul_f32 v[66:67], v[210:211], v[208:209] op_sel_hi:[0,1]
	v_add_f32_dpp v58, v58, v58 row_ror:8 row_mask:0xf bank_mask:0xf bound_ctrl:1
	v_pk_fma_f32 v[64:65], v[52:53], v[190:191], v[64:65]
	v_pk_fma_f32 v[66:67], v[48:49], v[192:193], v[66:67]
	v_add_f32_dpp v58, v58, v58 row_ror:4 row_mask:0xf bank_mask:0xf bound_ctrl:1
	v_add_f32_dpp v60, v59, v59 row_ror:8 row_mask:0xf bank_mask:0xf bound_ctrl:1
	s_nop 0
	v_add_f32_dpp v58, v58, v58 row_ror:2 row_mask:0xf bank_mask:0xf bound_ctrl:1
	v_fma_f32 v62, v210, v235, v60
	s_nop 0
	v_add_f32_dpp v58, v58, v58 row_ror:1 row_mask:0xf bank_mask:0xf bound_ctrl:1
	v_pk_fma_f32 v[52:53], v[58:59], v[202:203], v[64:65] op_sel_hi:[0,1,1]
	v_pk_fma_f32 v[48:49], v[58:59], v[204:205], v[66:67] op_sel_hi:[0,1,1]
	v_fma_f32 v62, v58, v234, v62
	ds_read_b32 v186, v97 offset:38000
	ds_write2st64_b32 v99, v61, v62 offset0:48 offset1:50
	s_waitcnt lgkmcnt(7)
	v_pk_mul_f32 v[58:59], v[52:53], v[32:33] op_sel_hi:[0,1]
	ds_read2_b64 v[232:235], v240 offset1:170
	v_add_u32_e32 v240, 0xaa0, v240
	ds_read_b128 v[194:197], v96 offset:38336
	ds_read_b128 v[198:201], v96 offset:38592
	v_pk_fma_f32 v[58:59], v[52:53], v[34:35], v[58:59] op_sel:[1,0,0]
	ds_read_b128 v[190:193], v96 offset:38080
	ds_read_b128 v[206:209], v96 offset:39104
	v_pk_fma_f32 v[58:59], v[48:49], v[36:37], v[58:59] op_sel_hi:[0,1,1]
	ds_read_b128 v[202:205], v96 offset:38848
	v_pk_fma_f32 v[58:59], v[48:49], v[38:39], v[58:59] op_sel:[1,0,0]
	v_pk_mul_f32 v[64:65], v[54:55], v[44:45] op_sel_hi:[0,1]
	v_pk_mul_f32 v[66:67], v[54:55], v[46:47] op_sel_hi:[0,1]
	v_add_f32_dpp v58, v58, v58 row_ror:8 row_mask:0xf bank_mask:0xf bound_ctrl:1
	v_pk_fma_f32 v[64:65], v[52:53], v[28:29], v[64:65]
	v_pk_fma_f32 v[66:67], v[48:49], v[30:31], v[66:67]
	v_add_f32_dpp v58, v58, v58 row_ror:4 row_mask:0xf bank_mask:0xf bound_ctrl:1
	v_add_f32_dpp v60, v59, v59 row_ror:8 row_mask:0xf bank_mask:0xf bound_ctrl:1
	s_nop 0
	v_add_f32_dpp v58, v58, v58 row_ror:2 row_mask:0xf bank_mask:0xf bound_ctrl:1
	v_fma_f32 v61, v54, v237, v60
	s_nop 0
	v_add_f32_dpp v58, v58, v58 row_ror:1 row_mask:0xf bank_mask:0xf bound_ctrl:1
	v_pk_fma_f32 v[52:53], v[58:59], v[40:41], v[64:65] op_sel_hi:[0,1,1]
	v_pk_fma_f32 v[48:49], v[58:59], v[42:43], v[66:67] op_sel_hi:[0,1,1]
	v_fma_f32 v61, v58, v236, v61
	ds_read_b32 v210, v97 offset:39360
	s_waitcnt lgkmcnt(8)
	v_pk_mul_f32 v[58:59], v[52:53], v[170:171] op_sel_hi:[0,1]
	ds_read_b128 v[32:35], v96 offset:39696
	ds_read_b128 v[36:39], v96 offset:39952
	v_pk_fma_f32 v[58:59], v[52:53], v[172:173], v[58:59] op_sel:[1,0,0]
	ds_read_b128 v[28:31], v96 offset:39440
	ds_read_b128 v[44:47], v96 offset:40464
	v_pk_fma_f32 v[58:59], v[48:49], v[174:175], v[58:59] op_sel_hi:[0,1,1]
	ds_read_b128 v[40:43], v96 offset:40208
	v_pk_fma_f32 v[58:59], v[48:49], v[176:177], v[58:59] op_sel:[1,0,0]
	v_pk_mul_f32 v[64:65], v[186:187], v[182:183] op_sel_hi:[0,1]
	v_pk_mul_f32 v[66:67], v[186:187], v[184:185] op_sel_hi:[0,1]
	v_add_f32_dpp v58, v58, v58 row_ror:8 row_mask:0xf bank_mask:0xf bound_ctrl:1
	v_pk_fma_f32 v[64:65], v[52:53], v[166:167], v[64:65]
	v_pk_fma_f32 v[66:67], v[48:49], v[168:169], v[66:67]
	v_add_f32_dpp v58, v58, v58 row_ror:4 row_mask:0xf bank_mask:0xf bound_ctrl:1
	v_add_f32_dpp v60, v59, v59 row_ror:8 row_mask:0xf bank_mask:0xf bound_ctrl:1
	s_nop 0
	v_add_f32_dpp v58, v58, v58 row_ror:2 row_mask:0xf bank_mask:0xf bound_ctrl:1
	v_fma_f32 v62, v186, v239, v60
	s_nop 0
	v_add_f32_dpp v58, v58, v58 row_ror:1 row_mask:0xf bank_mask:0xf bound_ctrl:1
	v_pk_fma_f32 v[52:53], v[58:59], v[178:179], v[64:65] op_sel_hi:[0,1,1]
	v_pk_fma_f32 v[48:49], v[58:59], v[180:181], v[66:67] op_sel_hi:[0,1,1]
	v_fma_f32 v62, v58, v238, v62
	ds_read_b32 v54, v97 offset:40720
	ds_write2st64_b32 v99, v61, v62 offset0:52 offset1:54
	s_waitcnt lgkmcnt(7)
	v_pk_mul_f32 v[58:59], v[52:53], v[194:195] op_sel_hi:[0,1]
	ds_read2_b64 v[236:239], v240 offset1:170
	v_add_u32_e32 v240, 0xaa0, v240
	ds_read_b128 v[170:173], v96 offset:41056
	ds_read_b128 v[174:177], v96 offset:41312
	v_pk_fma_f32 v[58:59], v[52:53], v[196:197], v[58:59] op_sel:[1,0,0]
	ds_read_b128 v[166:169], v96 offset:40800
	ds_read_b128 v[182:185], v96 offset:41824
	v_pk_fma_f32 v[58:59], v[48:49], v[198:199], v[58:59] op_sel_hi:[0,1,1]
	ds_read_b128 v[178:181], v96 offset:41568
	v_pk_fma_f32 v[58:59], v[48:49], v[200:201], v[58:59] op_sel:[1,0,0]
	v_pk_mul_f32 v[64:65], v[210:211], v[206:207] op_sel_hi:[0,1]
	v_pk_mul_f32 v[66:67], v[210:211], v[208:209] op_sel_hi:[0,1]
	v_add_f32_dpp v58, v58, v58 row_ror:8 row_mask:0xf bank_mask:0xf bound_ctrl:1
	v_pk_fma_f32 v[64:65], v[52:53], v[190:191], v[64:65]
	v_pk_fma_f32 v[66:67], v[48:49], v[192:193], v[66:67]
	v_add_f32_dpp v58, v58, v58 row_ror:4 row_mask:0xf bank_mask:0xf bound_ctrl:1
	v_add_f32_dpp v60, v59, v59 row_ror:8 row_mask:0xf bank_mask:0xf bound_ctrl:1
	s_nop 0
	v_add_f32_dpp v58, v58, v58 row_ror:2 row_mask:0xf bank_mask:0xf bound_ctrl:1
	v_fma_f32 v61, v210, v233, v60
	s_nop 0
	v_add_f32_dpp v58, v58, v58 row_ror:1 row_mask:0xf bank_mask:0xf bound_ctrl:1
	v_pk_fma_f32 v[52:53], v[58:59], v[202:203], v[64:65] op_sel_hi:[0,1,1]
	v_pk_fma_f32 v[48:49], v[58:59], v[204:205], v[66:67] op_sel_hi:[0,1,1]
	v_fma_f32 v61, v58, v232, v61
	ds_read_b32 v186, v97 offset:42080
	s_waitcnt lgkmcnt(8)
	v_pk_mul_f32 v[58:59], v[52:53], v[32:33] op_sel_hi:[0,1]
	ds_read_b128 v[194:197], v96 offset:42416
	ds_read_b128 v[198:201], v96 offset:42672
	v_pk_fma_f32 v[58:59], v[52:53], v[34:35], v[58:59] op_sel:[1,0,0]
	ds_read_b128 v[190:193], v96 offset:42160
	ds_read_b128 v[206:209], v96 offset:43184
	v_pk_fma_f32 v[58:59], v[48:49], v[36:37], v[58:59] op_sel_hi:[0,1,1]
	ds_read_b128 v[202:205], v96 offset:42928
	v_pk_fma_f32 v[58:59], v[48:49], v[38:39], v[58:59] op_sel:[1,0,0]
	v_pk_mul_f32 v[64:65], v[54:55], v[44:45] op_sel_hi:[0,1]
	v_pk_mul_f32 v[66:67], v[54:55], v[46:47] op_sel_hi:[0,1]
	v_add_f32_dpp v58, v58, v58 row_ror:8 row_mask:0xf bank_mask:0xf bound_ctrl:1
	v_pk_fma_f32 v[64:65], v[52:53], v[28:29], v[64:65]
	v_pk_fma_f32 v[66:67], v[48:49], v[30:31], v[66:67]
	v_add_f32_dpp v58, v58, v58 row_ror:4 row_mask:0xf bank_mask:0xf bound_ctrl:1
	v_add_f32_dpp v60, v59, v59 row_ror:8 row_mask:0xf bank_mask:0xf bound_ctrl:1
	s_nop 0
	v_add_f32_dpp v58, v58, v58 row_ror:2 row_mask:0xf bank_mask:0xf bound_ctrl:1
	v_fma_f32 v62, v54, v235, v60
	s_nop 0
	v_add_f32_dpp v58, v58, v58 row_ror:1 row_mask:0xf bank_mask:0xf bound_ctrl:1
	v_pk_fma_f32 v[52:53], v[58:59], v[40:41], v[64:65] op_sel_hi:[0,1,1]
	v_pk_fma_f32 v[48:49], v[58:59], v[42:43], v[66:67] op_sel_hi:[0,1,1]
	v_fma_f32 v62, v58, v234, v62
	ds_read_b32 v210, v97 offset:43440
	ds_write2st64_b32 v99, v61, v62 offset0:56 offset1:58
	s_waitcnt lgkmcnt(7)
	v_pk_mul_f32 v[58:59], v[52:53], v[170:171] op_sel_hi:[0,1]
	v_pk_fma_f32 v[58:59], v[52:53], v[172:173], v[58:59] op_sel:[1,0,0]
	v_pk_fma_f32 v[58:59], v[48:49], v[174:175], v[58:59] op_sel_hi:[0,1,1]
	v_pk_fma_f32 v[58:59], v[48:49], v[176:177], v[58:59] op_sel:[1,0,0]
	v_pk_mul_f32 v[64:65], v[186:187], v[182:183] op_sel_hi:[0,1]
	v_pk_mul_f32 v[66:67], v[186:187], v[184:185] op_sel_hi:[0,1]
	v_add_f32_dpp v58, v58, v58 row_ror:8 row_mask:0xf bank_mask:0xf bound_ctrl:1
	v_pk_fma_f32 v[64:65], v[52:53], v[166:167], v[64:65]
	v_pk_fma_f32 v[66:67], v[48:49], v[168:169], v[66:67]
	v_add_f32_dpp v58, v58, v58 row_ror:4 row_mask:0xf bank_mask:0xf bound_ctrl:1
	v_add_f32_dpp v60, v59, v59 row_ror:8 row_mask:0xf bank_mask:0xf bound_ctrl:1
	s_nop 0
	v_add_f32_dpp v58, v58, v58 row_ror:2 row_mask:0xf bank_mask:0xf bound_ctrl:1
	v_fma_f32 v61, v186, v237, v60
	s_nop 0
	v_add_f32_dpp v58, v58, v58 row_ror:1 row_mask:0xf bank_mask:0xf bound_ctrl:1
	v_pk_fma_f32 v[52:53], v[58:59], v[178:179], v[64:65] op_sel_hi:[0,1,1]
	v_pk_fma_f32 v[48:49], v[58:59], v[180:181], v[66:67] op_sel_hi:[0,1,1]
	v_fma_f32 v61, v58, v236, v61
	s_waitcnt lgkmcnt(1)
	v_pk_mul_f32 v[58:59], v[52:53], v[194:195] op_sel_hi:[0,1]
	v_pk_fma_f32 v[58:59], v[52:53], v[196:197], v[58:59] op_sel:[1,0,0]
	v_pk_fma_f32 v[58:59], v[48:49], v[198:199], v[58:59] op_sel_hi:[0,1,1]
	v_pk_fma_f32 v[58:59], v[48:49], v[200:201], v[58:59] op_sel:[1,0,0]
	v_pk_mul_f32 v[64:65], v[210:211], v[206:207] op_sel_hi:[0,1]
	v_pk_mul_f32 v[66:67], v[210:211], v[208:209] op_sel_hi:[0,1]
	v_add_f32_dpp v58, v58, v58 row_ror:8 row_mask:0xf bank_mask:0xf bound_ctrl:1
	v_pk_fma_f32 v[64:65], v[52:53], v[190:191], v[64:65]
	v_pk_fma_f32 v[66:67], v[48:49], v[192:193], v[66:67]
	v_add_f32_dpp v58, v58, v58 row_ror:4 row_mask:0xf bank_mask:0xf bound_ctrl:1
	v_add_f32_dpp v60, v59, v59 row_ror:8 row_mask:0xf bank_mask:0xf bound_ctrl:1
	s_nop 0
	v_add_f32_dpp v58, v58, v58 row_ror:2 row_mask:0xf bank_mask:0xf bound_ctrl:1
	v_fma_f32 v62, v210, v239, v60
	s_nop 0
	v_add_f32_dpp v58, v58, v58 row_ror:1 row_mask:0xf bank_mask:0xf bound_ctrl:1
	v_pk_fma_f32 v[52:53], v[58:59], v[202:203], v[64:65] op_sel_hi:[0,1,1]
	v_pk_fma_f32 v[48:49], v[58:59], v[204:205], v[66:67] op_sel_hi:[0,1,1]
	v_fma_f32 v62, v58, v238, v62
	ds_write2st64_b32 v99, v61, v62 offset0:60 offset1:62
	s_setprio 0
	s_mov_b64 s[78:79], 0
